# P10-epilogue-issue-row-scale-loads-before-conv-weight-loads
# speedup vs baseline: 1.0056x; 1.0056x over previous
; #define LAS __attribute__((address_space(3)))
;     __device__ __forceinline__ void operator()(const pg8::f32x4 (&acc)[2][2][4][2], const pg8::Unit& u, int wr, int wc, int fr_, int fq_) const {
;     ...
;         const int acol0 = u.pn * 128, cl0_ = wc * 32 + 8 * fq;
;         for (int e = tid; e < 1024; e += 512) { const int k = e >> 8, cl = e & 255, gcol = (cl >> 7) * DFF + acol0 + (cl & 127); CW[e] = (k < 3) ? conv_w[k * UPW + gcol] : conv_b[gcol]; }
;         LAS float* RSL = BD + 2048;
;         if (tid < 256) RSL[tid] = row_rs(SS, u.pm * 256 + tid);
.LBB0_2579:
	v_mov_b32_e32 v196, v0
	v_readlane_b32 s98, v255, 28
	v_readlane_b32 s99, v255, 29
	v_lshl_add_u32 v160, s28, 8, v196
	v_ashrrev_i32_e32 v161, 31, v160
	v_lshlrev_b64 v[160:161], 6, v[160:161]
	v_cmp_gt_i32_e32 vcc, 0x100, v196
	v_lshl_add_u64 v[160:161], s[98:99], 0, v[160:161]
	s_and_saveexec_b64 s[100:101], vcc
	global_load_dwordx4 v[238:241], v[160:161], off offset:48
	global_load_dwordx4 v[242:245], v[160:161], off offset:32
	global_load_dwordx4 v[246:249], v[160:161], off offset:16
	global_load_dwordx4 v[250:253], v[160:161], off
	s_mov_b64 exec, s[100:101]
	s_lshl_b32 s36, s0, 7
	s_movk_i32 s0, 0x400
	v_mov_b32_e32 v199, v1
	v_mov_b32_e32 v132, v220
	v_cmp_gt_i32_e32 vcc, s0, v196
	s_and_saveexec_b64 s[0:1], vcc
	v_readlane_b32 s60, v254, 63
	v_readlane_b32 s61, v255, 0
	v_readlane_b32 s62, v255, 1
	v_readlane_b32 s63, v255, 2
	v_readlane_b32 s64, v255, 3
	v_readlane_b32 s65, v255, 4
	v_readlane_b32 s66, v255, 5
	v_readlane_b32 s67, v255, 6
	v_readlane_b32 s68, v255, 7
	v_readlane_b32 s69, v255, 8
	v_readlane_b32 s70, v255, 9
	v_readlane_b32 s71, v255, 10
	v_readlane_b32 s72, v255, 11
	v_readlane_b32 s73, v255, 12
	v_readlane_b32 s74, v255, 13
	v_readlane_b32 s75, v255, 14
	s_cbranch_execz .LBB0_2591
	v_and_b32_e32 v130, 0x7f, v196
	v_or_b32_e32 v133, s36, v130
	v_max_i32_e32 v130, 0x200, v196
	v_sub_u32_e32 v130, v130, v196
	v_add_u32_e32 v131, 0x1ff, v130
	v_cmp_lt_u32_e32 vcc, s21, v131
	s_mov_b64 s[2:3], -1
	v_mov_b32_e32 v130, v196
	s_and_saveexec_b64 s[4:5], vcc
	s_cbranch_execz .LBB0_2588
	v_lshrrev_b32_e32 v134, 9, v131
	v_add_u32_e32 v197, 0x200, v196
	v_add_u32_e32 v135, -1, v134
	v_cmp_lt_u32_e32 vcc, 1, v135
	v_mov_b32_e32 v136, 0
	v_mov_b64_e32 v[130:131], v[196:197]
	s_and_saveexec_b64 s[6:7], vcc
	s_cbranch_execz .LBB0_2585
	v_lshrrev_b32_e32 v130, 1, v135
	v_add_u32_e32 v130, 1, v130
	v_readlane_b32 s2, v255, 41
	v_readlane_b32 s60, v254, 63
	v_and_b32_e32 v136, -2, v130
	v_lshl_add_u32 v137, v196, 2, s2
	s_mov_b32 s13, 0
	s_mov_b64 s[16:17], 0
	v_mov_b64_e32 v[130:131], v[196:197]
	v_readlane_b32 s62, v255, 1
	v_readlane_b32 s63, v255, 2
	v_readlane_b32 s64, v255, 3
	v_readlane_b32 s65, v255, 4
	v_readlane_b32 s61, v255, 0
	v_readlane_b32 s66, v255, 5
	v_readlane_b32 s67, v255, 6
	v_readlane_b32 s68, v255, 7
	v_readlane_b32 s69, v255, 8
	v_readlane_b32 s70, v255, 9
	v_readlane_b32 s71, v255, 10
	v_readlane_b32 s72, v255, 11
	v_readlane_b32 s73, v255, 12
	v_readlane_b32 s74, v255, 13
	v_readlane_b32 s75, v255, 14

; #define GAS __attribute__((address_space(1)))
; __device__ __forceinline__ float row_rs(const float* SS, int row) {
;     const f32x4 a = *(const GAS f32x4*)(SS + (size_t)row * 16), b = *(const GAS f32x4*)(SS + (size_t)row * 16 + 4), c = *(const GAS f32x4*)(SS + (size_t)row * 16 + 8), d = *(const GAS f32x4*)(SS + (size_t)row * 16 + 12);
;     const float s = ((a[0] + a[1]) + (a[2] + a[3])) + ((b[0] + b[1]) + (b[2] + b[3])) + ((c[0] + c[1]) + (c[2] + c[3])) + ((d[0] + d[1]) + (d[2] + d[3]));
;     return __builtin_amdgcn_rsqf(s * (1.f / D) + EPS);
;     __device__ __forceinline__ void operator()(const pg8::f32x4 (&acc)[2][2][4][2], const pg8::Unit& u, int wr, int wc, int fr_, int fq_) const {
;     ...
;         if (tid < 256) RSL[tid] = row_rs(SS, u.pm * 256 + tid);
.LBB0_2591:
	s_or_b64 exec, exec, s[0:1]
	s_movk_i32 s0, 0x100
	v_cmp_gt_i32_e32 vcc, s0, v196
	s_and_saveexec_b64 s[0:1], vcc
	s_cbranch_execz .LBB0_2593
	s_waitcnt vmcnt(0)
	v_add_f32_e32 v242, v242, v243
	v_add_f32_e32 v244, v244, v245
	v_mov_b32_e32 v130, v251
	v_mov_b32_e32 v131, v252
	v_mov_b32_e32 v251, v253
	v_pk_add_f32 v[130:131], v[130:131], v[250:251]
	v_mov_b32_e32 v250, v247
	v_mov_b32_e32 v251, v248
	v_mov_b32_e32 v247, v249
	v_pk_add_f32 v[246:247], v[250:251], v[246:247]
	v_pk_add_f32 v[130:131], v[130:131], v[130:131] op_sel:[0,1] op_sel_hi:[1,0]
	v_pk_add_f32 v[246:247], v[246:247], v[246:247] op_sel:[0,1] op_sel_hi:[1,0]
	v_mov_b32_e32 v131, v238
	v_mov_b32_e32 v247, v239
	v_mov_b32_e32 v243, v240
	v_mov_b32_e32 v245, v241
	v_pk_add_f32 v[130:131], v[130:131], v[246:247]
	v_pk_add_f32 v[238:239], v[242:243], v[244:245]
	s_nop 0
	v_pk_add_f32 v[130:131], v[130:131], v[238:239]
	s_nop 0
	v_add_f32_e32 v130, v130, v131
	v_fmamk_f32 v130, v130, 0x3a800000, v225
	v_rsq_f32_e32 v130, v130
	v_lshl_add_u32 v131, v196, 2, 0
	v_add_u32_e32 v131, 0x23000, v131
	ds_write_b32 v131, v130
